# attention item staging without per-lane masking: jmin is 0 or 128 and a wave-instruction covers 64 key rows, so the first two row groups are written only when jmin == 0
# speedup vs baseline: 1.0024x; 1.0024x over previous
.Lstg_from2:
	ds_write_b128 v232, v[38:41] offset:18432
	ds_write_b128 v233, v[34:37] offset:18432
	ds_write_b128 v232, v[46:49] offset:27648
	ds_write_b128 v233, v[42:45] offset:27648
	ds_write_b128 v232, v[54:57] offset:36864
	ds_write_b128 v233, v[50:53] offset:36864
	ds_write_b128 v232, v[62:65] offset:46080
	ds_write_b128 v233, v[58:61] offset:46080
	v_readlane_b32 s6, v255, 2
	s_add_i32 s40, s40, s6
	s_cmp_ge_i32 s40, s3
	s_cselect_b64 s[26:27], -1, 0
	s_and_b64 vcc, exec, s[26:27]
	s_waitcnt lgkmcnt(0)
	s_barrier
	s_cbranch_vccnz .LBB0_360
	s_and_b64 vcc, exec, s[4:5]
	s_mov_b32 s6, s40
	s_cbranch_vccnz .LBB0_347
	s_mul_hi_i32 s6, s40, 0x2aaaaaab
	s_lshr_b32 s7, s6, 31
	s_ashr_i32 s6, s6, 3
	s_add_i32 s6, s6, s7
	s_lshl_b32 s7, s6, 3
	v_readlane_b32 s9, v255, 3
	s_or_b32 s7, s7, s9
	s_mul_i32 s6, s6, 48
	s_mul_i32 s7, s7, 48
	s_sub_i32 s6, s40, s6
	s_add_i32 s6, s7, s6
